# global barriers: first local arriver of each XCC starts an extra L2 writeback while it waits (v56 + earlywb)
# speedup vs baseline: 1.0022x; 1.0022x over previous
; __device__ __forceinline__ unsigned xb_ld(unsigned* p)              { return __hip_atomic_load(p, __ATOMIC_RELAXED, __HIP_MEMORY_SCOPE_AGENT); }
; __device__ __forceinline__ unsigned xb_add(unsigned* p, unsigned v) { return __hip_atomic_fetch_add(p, v, __ATOMIC_RELAXED, __HIP_MEMORY_SCOPE_AGENT); }
; #define XB_SPIN(cond, bar) do { unsigned _sp = 0; while (cond) { __builtin_amdgcn_s_sleep(1); \
;     if ((++_sp & 255u) == 0u) { if (xb_ld(&(bar)[XB_TMO])) break; if (_sp > XB_SPIN_CAP) { atomicAdd(&(bar)[XB_TMO], 1u); break; } } } } while (0)
; __device__ __forceinline__ void xcd_barrier(const XcdBarrier& b) {
;     ...
;         const unsigned old = xb_add(&bar[XB_XSUB(b.x)], 1u);
;         const unsigned gen = old / nloc;
;         if (old + 1u == (gen + 1u) * nloc) {
;             __builtin_amdgcn_fence(__ATOMIC_RELEASE, "agent");
;             asm volatile("s_waitcnt vmcnt(0)" ::: "memory");
;             const unsigned og = xb_add(&bar[XB_TOP], 1u);
;             const unsigned tg = og / nx;
;             if (og + 1u == (tg + 1u) * nx) xb_add(&bar[XB_TOPGEN], 1u);
;             else XB_SPIN(xb_ld(&bar[XB_TOPGEN]) == tg, bar);
;             __builtin_amdgcn_fence(__ATOMIC_ACQUIRE, "agent");
;             xb_add(&bar[XB_XGEN(b.x)], 1u);
;             asm volatile("s_waitcnt vmcnt(0)" ::: "memory");
;         } else {
;             XB_SPIN(xb_ld(&bar[XB_XGEN(b.x)]) == gen, bar);
;             __builtin_amdgcn_fence(__ATOMIC_ACQUIRE, "agent");
;             asm volatile("s_waitcnt vmcnt(0)" ::: "memory");
;         }
.LBB0_66:
	s_or_b64 exec, exec, s[14:15]
	buffer_inv sc1
	v_cvt_f32_u32_e32 v4, v2
	s_waitcnt vmcnt(1)
	v_readfirstlane_b32 s4, v3
	v_sub_u32_e32 v3, 0, v2
	v_rcp_iflag_f32_e32 v4, v4
	v_add_u32_e32 v5, s4, v1
	v_mul_f32_e32 v4, 0x4f7ffffe, v4
	v_cvt_u32_f32_e32 v4, v4
	v_mul_lo_u32 v1, v3, v4
	v_mul_hi_u32 v1, v4, v1
	v_add_u32_e32 v1, v4, v1
	v_mul_hi_u32 v1, v5, v1
	v_mul_lo_u32 v3, v1, v2
	v_sub_u32_e32 v3, v5, v3
	v_add_u32_e32 v4, 1, v1
	v_cmp_ge_u32_e32 vcc, v3, v2
	s_nop 1
	v_cndmask_b32_e32 v1, v1, v4, vcc
	v_sub_u32_e32 v4, v3, v2
	v_cndmask_b32_e32 v3, v3, v4, vcc
	v_add_u32_e32 v4, 1, v1
	v_cmp_ge_u32_e32 vcc, v3, v2
	v_add_u32_e32 v3, 1, v5
	s_nop 0
	v_cndmask_b32_e32 v1, v1, v4, vcc
	v_mul_lo_u32 v4, v2, v1
	v_add_u32_e32 v2, v4, v2
	v_cmp_ne_u32_e32 vcc, v3, v2
	v_mov_b32_e32 v250, v1
	s_and_saveexec_b64 s[4:5], vcc
	s_xor_b64 s[14:15], exec, s[4:5]
	s_cbranch_execz .LBB0_80
	v_sub_u32_e32 v251, v5, v4
	v_cmp_ne_u32_e32 vcc, 0, v251
	s_cbranch_vccnz .Lxb_noearly_0
	buffer_wbl2 sc1
.Lxb_noearly_0:
	v_readlane_b32 s4, v245, 18
	s_waitcnt lgkmcnt(0)
	v_mov_b32_e32 v0, 0
	v_readlane_b32 s5, v245, 19
	s_nop 4
	global_load_dword v2, v0, s[4:5] sc1
	s_waitcnt vmcnt(0)
	v_cmp_eq_u32_e32 vcc, v2, v1
	s_and_saveexec_b64 s[18:19], vcc
	s_cbranch_execz .LBB0_79
	s_mov_b32 s4, 1
	s_mov_b64 s[20:21], 0
	s_branch .LBB0_70

; __device__ __forceinline__ unsigned xb_ld(unsigned* p)              { return __hip_atomic_load(p, __ATOMIC_RELAXED, __HIP_MEMORY_SCOPE_AGENT); }
; __device__ __forceinline__ unsigned xb_add(unsigned* p, unsigned v) { return __hip_atomic_fetch_add(p, v, __ATOMIC_RELAXED, __HIP_MEMORY_SCOPE_AGENT); }
; #define XB_SPIN(cond, bar) do { unsigned _sp = 0; while (cond) { __builtin_amdgcn_s_sleep(1); \
;     if ((++_sp & 255u) == 0u) { if (xb_ld(&(bar)[XB_TMO])) break; if (_sp > XB_SPIN_CAP) { atomicAdd(&(bar)[XB_TMO], 1u); break; } } } } while (0)
; __device__ __forceinline__ void xcd_barrier(const XcdBarrier& b) {
;     ...
;         const unsigned old = xb_add(&bar[XB_XSUB(b.x)], 1u);
;         const unsigned gen = old / nloc;
;         if (old + 1u == (gen + 1u) * nloc) {
;             __builtin_amdgcn_fence(__ATOMIC_RELEASE, "agent");
;             asm volatile("s_waitcnt vmcnt(0)" ::: "memory");
;             const unsigned og = xb_add(&bar[XB_TOP], 1u);
;             const unsigned tg = og / nx;
;             if (og + 1u == (tg + 1u) * nx) xb_add(&bar[XB_TOPGEN], 1u);
;             else XB_SPIN(xb_ld(&bar[XB_TOPGEN]) == tg, bar);
;             __builtin_amdgcn_fence(__ATOMIC_ACQUIRE, "agent");
;             xb_add(&bar[XB_XGEN(b.x)], 1u);
;             asm volatile("s_waitcnt vmcnt(0)" ::: "memory");
;         } else {
;             XB_SPIN(xb_ld(&bar[XB_XGEN(b.x)]) == gen, bar);
.LBB0_468:
	s_or_b64 exec, exec, s[16:17]
	buffer_inv sc1
	v_cvt_f32_u32_e32 v5, v3
	s_waitcnt vmcnt(1)
	v_readfirstlane_b32 s16, v4
	v_sub_u32_e32 v4, 0, v3
	v_rcp_iflag_f32_e32 v5, v5
	v_add_u32_e32 v6, s16, v0
	v_mul_f32_e32 v5, 0x4f7ffffe, v5
	v_cvt_u32_f32_e32 v5, v5
	v_mul_lo_u32 v0, v4, v5
	v_mul_hi_u32 v0, v5, v0
	v_add_u32_e32 v0, v5, v0
	v_mul_hi_u32 v0, v6, v0
	v_mul_lo_u32 v4, v0, v3
	v_sub_u32_e32 v4, v6, v4
	v_add_u32_e32 v5, 1, v0
	v_cmp_ge_u32_e32 vcc, v4, v3
	s_nop 1
	v_cndmask_b32_e32 v0, v0, v5, vcc
	v_sub_u32_e32 v5, v4, v3
	v_cndmask_b32_e32 v4, v4, v5, vcc
	v_add_u32_e32 v5, 1, v0
	v_cmp_ge_u32_e32 vcc, v4, v3
	v_add_u32_e32 v4, 1, v6
	s_nop 0
	v_cndmask_b32_e32 v0, v0, v5, vcc
	v_mul_lo_u32 v5, v3, v0
	v_add_u32_e32 v3, v5, v3
	v_cmp_ne_u32_e32 vcc, v4, v3
	v_mov_b32_e32 v250, v0
	s_and_saveexec_b64 s[16:17], vcc
	s_xor_b64 s[36:37], exec, s[16:17]
	s_cbranch_execz .LBB0_482
	v_sub_u32_e32 v251, v6, v5
	v_cmp_ne_u32_e32 vcc, 0, v251
	s_cbranch_vccnz .Lxb_noearly_1
	buffer_wbl2 sc1
.Lxb_noearly_1:
	v_readlane_b32 s16, v245, 18
	v_readlane_b32 s17, v245, 19
	s_waitcnt lgkmcnt(0)
	s_nop 3
	global_load_dword v2, v1, s[16:17] sc1
	s_waitcnt vmcnt(0)
	v_cmp_eq_u32_e32 vcc, v2, v0
	s_and_saveexec_b64 s[38:39], vcc
	s_cbranch_execz .LBB0_481
	s_mov_b32 s23, 1
	s_mov_b64 s[40:41], 0
	s_branch .LBB0_472

; __device__ __forceinline__ unsigned xb_ld(unsigned* p)              { return __hip_atomic_load(p, __ATOMIC_RELAXED, __HIP_MEMORY_SCOPE_AGENT); }
; __device__ __forceinline__ unsigned xb_add(unsigned* p, unsigned v) { return __hip_atomic_fetch_add(p, v, __ATOMIC_RELAXED, __HIP_MEMORY_SCOPE_AGENT); }
; #define XB_SPIN(cond, bar) do { unsigned _sp = 0; while (cond) { __builtin_amdgcn_s_sleep(1); \
;     if ((++_sp & 255u) == 0u) { if (xb_ld(&(bar)[XB_TMO])) break; if (_sp > XB_SPIN_CAP) { atomicAdd(&(bar)[XB_TMO], 1u); break; } } } } while (0)
; __device__ __forceinline__ void xcd_barrier(const XcdBarrier& b) {
;     ...
;         const unsigned old = xb_add(&bar[XB_XSUB(b.x)], 1u);
;         const unsigned gen = old / nloc;
;         if (old + 1u == (gen + 1u) * nloc) {
;             __builtin_amdgcn_fence(__ATOMIC_RELEASE, "agent");
;             asm volatile("s_waitcnt vmcnt(0)" ::: "memory");
;             const unsigned og = xb_add(&bar[XB_TOP], 1u);
;             const unsigned tg = og / nx;
;             if (og + 1u == (tg + 1u) * nx) xb_add(&bar[XB_TOPGEN], 1u);
;             else XB_SPIN(xb_ld(&bar[XB_TOPGEN]) == tg, bar);
;             __builtin_amdgcn_fence(__ATOMIC_ACQUIRE, "agent");
;             xb_add(&bar[XB_XGEN(b.x)], 1u);
;             asm volatile("s_waitcnt vmcnt(0)" ::: "memory");
;         } else {
;             XB_SPIN(xb_ld(&bar[XB_XGEN(b.x)]) == gen, bar);
.LBB0_752:
	s_or_b64 exec, exec, s[16:17]
	buffer_inv sc1
	v_cvt_f32_u32_e32 v5, v3
	s_waitcnt vmcnt(1)
	v_readfirstlane_b32 s16, v4
	v_sub_u32_e32 v4, 0, v3
	v_rcp_iflag_f32_e32 v5, v5
	v_add_u32_e32 v6, s16, v0
	v_mul_f32_e32 v5, 0x4f7ffffe, v5
	v_cvt_u32_f32_e32 v5, v5
	v_mul_lo_u32 v0, v4, v5
	v_mul_hi_u32 v0, v5, v0
	v_add_u32_e32 v0, v5, v0
	v_mul_hi_u32 v0, v6, v0
	v_mul_lo_u32 v4, v0, v3
	v_sub_u32_e32 v4, v6, v4
	v_add_u32_e32 v5, 1, v0
	v_cmp_ge_u32_e32 vcc, v4, v3
	s_nop 1
	v_cndmask_b32_e32 v0, v0, v5, vcc
	v_sub_u32_e32 v5, v4, v3
	v_cndmask_b32_e32 v4, v4, v5, vcc
	v_add_u32_e32 v5, 1, v0
	v_cmp_ge_u32_e32 vcc, v4, v3
	v_add_u32_e32 v4, 1, v6
	s_nop 0
	v_cndmask_b32_e32 v0, v0, v5, vcc
	v_mul_lo_u32 v5, v3, v0
	v_add_u32_e32 v3, v5, v3
	v_cmp_ne_u32_e32 vcc, v4, v3
	v_mov_b32_e32 v250, v0
	s_and_saveexec_b64 s[16:17], vcc
	s_xor_b64 s[18:19], exec, s[16:17]
	s_cbranch_execz .LBB0_766
	v_sub_u32_e32 v251, v6, v5
	v_cmp_ne_u32_e32 vcc, 0, v251
	s_cbranch_vccnz .Lxb_noearly_2
	buffer_wbl2 sc1
.Lxb_noearly_2:
	v_readlane_b32 s16, v245, 18
	v_readlane_b32 s17, v245, 19
	s_waitcnt lgkmcnt(0)
	s_nop 3
	global_load_dword v2, v1, s[16:17] sc1
	s_waitcnt vmcnt(0)
	v_cmp_eq_u32_e32 vcc, v2, v0
	s_and_saveexec_b64 s[20:21], vcc
	s_cbranch_execz .LBB0_765
	s_mov_b32 s42, 1
	s_mov_b64 s[22:23], 0
	s_branch .LBB0_756
